# weight-conversion and rms work items dealt wave-major across workgroups (balanced remainder)
# speedup vs baseline: 1.0165x; 1.0019x over previous
.LBB0_8:
	s_or_b64 exec, exec, s[12:13]
	s_load_dwordx16 s[36:51], s[0:1], 0x0
	s_ashr_i32 s0, s18, 6
	s_lshl_b32 s1, s2, 3
	s_lshl_b32 s12, s0, 8
	s_add_i32 s12, s12, s2
	s_lshl_b32 s75, s86, 3
	s_waitcnt lgkmcnt(0)
	v_writelane_b32 v250, s36, 1
	s_cmpk_gt_i32 s12, 0x187f
	v_and_b32_e32 v1, 63, v10
	v_writelane_b32 v250, s37, 2
	v_writelane_b32 v250, s38, 3
	v_writelane_b32 v250, s39, 4
	v_writelane_b32 v250, s40, 5
	v_writelane_b32 v250, s41, 6
	v_writelane_b32 v250, s42, 7
	v_writelane_b32 v250, s43, 8
	v_writelane_b32 v250, s44, 9
	v_writelane_b32 v250, s45, 10
	v_writelane_b32 v250, s46, 11
	v_writelane_b32 v250, s47, 12
	v_writelane_b32 v250, s48, 13
	v_writelane_b32 v250, s49, 14
	v_writelane_b32 v250, s50, 15
	v_writelane_b32 v250, s51, 16
	v_writelane_b32 v250, s1, 0
	s_cbranch_scc1 .LBB0_40
	s_add_u32 s14, s84, s4
	v_and_b32_e32 v2, 7, v10
	s_addc_u32 s15, s85, s5
	s_lshl_b32 s0, s0, 14
	v_lshlrev_b32_e32 v36, 4, v2
	v_mov_b32_e32 v37, 0
	v_readlane_b32 s36, v250, 1
	s_add_i32 s6, s0, 0
	v_mul_u32_u24_e32 v5, 0x420, v2
	v_lshl_add_u64 v[2:3], s[14:15], 0, v[36:37]
	s_mov_b64 s[0:1], 0x1700000
	v_readlane_b32 s38, v250, 3
	v_lshl_add_u64 v[38:39], v[2:3], 0, s[0:1]
	v_readlane_b32 s39, v250, 4
	s_add_u32 s14, s38, 0x2000
	s_mov_b64 s[0:1], 0xc00000
	s_addc_u32 s15, s39, 0
	v_lshl_add_u64 v[40:41], v[2:3], 0, s[0:1]
	s_mov_b64 s[0:1], 0xa00000
	v_lshrrev_b32_e32 v34, 3, v1
	v_lshl_add_u64 v[42:43], v[2:3], 0, s[0:1]
	s_cmp_lg_u64 s[38:39], 0
	s_mov_b64 s[0:1], 0x400000
	v_add_u32_e32 v57, s6, v36
	v_mul_u32_u24_e32 v4, 0x84, v34
	s_cselect_b64 s[16:17], -1, 0
	v_lshl_add_u64 v[44:45], v[2:3], 0, s[0:1]
	s_lshl_b32 s0, s12, 6
	v_lshlrev_b32_e32 v6, 2, v34
	v_readlane_b32 s37, v250, 2
	v_readlane_b32 s40, v250, 5
	v_readlane_b32 s41, v250, 6
	v_readlane_b32 s44, v250, 9
	v_readlane_b32 s45, v250, 10
	v_or_b32_e32 v62, 32, v34
	s_add_i32 s23, s0, 0x7ffff800
	s_lshl_b32 s0, s12, 1
	v_add_u32_e32 v67, v57, v4
	s_mov_b32 s7, 0
	v_or_b32_e32 v58, 8, v34
	v_or_b32_e32 v59, 16, v34
	v_or_b32_e32 v60, 24, v34
	v_add3_u32 v61, s6, v5, v6
	v_mul_u32_u24_e32 v63, 0x84, v62
	v_or_b32_e32 v64, 40, v34
	v_or_b32_e32 v65, 48, v34
	v_or_b32_e32 v66, 56, v34
	v_lshl_add_u64 v[46:47], s[92:93], 0, v[36:37]
	v_lshl_add_u64 v[48:49], s[90:91], 0, v[36:37]
	v_lshl_add_u64 v[50:51], s[44:45], 0, v[36:37]
	v_lshl_add_u64 v[52:53], s[40:41], 0, v[36:37]
	v_mov_b32_e32 v35, v37
	s_lshl_b32 s13, s12, 5
	s_lshl_b32 s22, s75, 5
	s_lshl_b32 s24, s75, 6
	s_add_i32 s25, s0, 0xfffff400
	s_lshl_b32 s26, s75, 1
	v_add_u32_e32 v68, 0x420, v67
	v_add_u32_e32 v69, 0x428, v67
	v_add_u32_e32 v70, 0x840, v67
	v_add_u32_e32 v71, 0x848, v67
	v_add_u32_e32 v72, 0xc60, v67
	v_add_u32_e32 v73, 0xc68, v67
	v_add_u32_e32 v74, 0x1080, v67
	v_add_u32_e32 v75, 0x1088, v67
	v_add_u32_e32 v76, 0x14a0, v67
	v_add_u32_e32 v77, 0x14a8, v67
	v_add_u32_e32 v78, 0x18c0, v67
	v_add_u32_e32 v79, 0x18c8, v67
	v_add_u32_e32 v80, 0x1ce0, v67
	v_add_u32_e32 v81, 0x1ce8, v67
	s_movk_i32 s27, 0x7fff
	s_mov_b32 s29, 0xffff0000
	s_movk_i32 s30, 0x5800
	s_mov_b32 s31, 0x2c000
	s_mov_b32 s33, 0x58000
	s_mov_b32 s34, 0x84000
	s_mov_b32 s35, 0xb0000
	s_mov_b32 s36, 0xdc000
	s_mov_b32 s37, 0x108000
	s_mov_b32 s38, 0x134000
	s_movk_i32 s39, 0x3000
	s_mov_b32 s40, s12
	v_readlane_b32 s42, v250, 7
	v_readlane_b32 s43, v250, 8
	v_readlane_b32 s46, v250, 11
	v_readlane_b32 s47, v250, 12
	v_readlane_b32 s48, v250, 13
	v_readlane_b32 s49, v250, 14
	v_readlane_b32 s50, v250, 15
	v_readlane_b32 s51, v250, 16
	s_branch .LBB0_12

.LBB0_212:
	s_add_i32 s28, s46, 1
	s_cmp_lg_u32 s46, 3
	s_cselect_b64 s[42:43], -1, 0
	s_cmp_eq_u32 s46, 3
	s_cselect_b64 s[44:45], -1, 0
	s_and_b64 vcc, exec, s[44:45]
	s_waitcnt lgkmcnt(0)
	s_barrier
	s_cbranch_vccnz .LBB0_280
	s_ashr_i32 s8, s10, 6
	s_lshl_b32 s4, s8, 8
	s_add_i32 s10, s4, s2
	s_cmp_lg_u32 s46, 0
	s_cselect_b64 s[38:39], -1, 0
	s_cmp_eq_u32 s28, 2
	s_cselect_b64 s[6:7], -1, 0
	s_and_b64 s[4:5], s[6:7], exec
	s_cselect_b32 s9, 0x400, 0
	s_cmp_eq_u32 s46, 0
	s_cselect_b64 s[4:5], -1, 0
	s_and_b64 s[12:13], s[4:5], exec
	s_cselect_b32 s11, 0, 0x200
	s_cselect_b32 s12, 0x600, s9
	s_add_i32 s13, s11, s12
	s_addk_i32 s13, 0x1280
	s_cmp_ge_i32 s10, s13
	s_cbranch_scc1 .LBB0_280
	s_mov_b32 s18, s28
	v_readlane_b32 s48, v250, 1
	s_lshl_b64 s[14:15], s[18:19], 14
	v_readlane_b32 s50, v250, 3
	v_readlane_b32 s51, v250, 4
	s_add_u32 s40, s50, s14
	s_addc_u32 s41, s51, s15
	s_lshl_b32 s8, s8, 14
	s_add_i32 s14, s8, 0
	v_readlane_b32 s8, v248, 0
	v_readlane_b32 s9, v248, 1
	s_and_b64 s[8:9], s[8:9], exec
	s_mov_b32 s8, 0x400000
	s_cselect_b32 s8, 0x1d00000, s8
	s_add_u32 s8, s16, s8
	v_and_b32_e32 v1, 7, v158
	s_addc_u32 s9, s17, 0
	v_lshlrev_b32_e32 v2, 4, v1
	v_lshl_add_u64 v[36:37], s[8:9], 0, v[2:3]
	s_mov_b64 s[8:9], 0x1300000
	v_lshl_add_u64 v[38:39], v[36:37], 0, s[8:9]
	s_add_u32 s30, s40, 0x2000
	s_mov_b64 s[8:9], 0x800000
	s_addc_u32 s31, s41, 0
	v_lshl_add_u64 v[40:41], v[36:37], 0, s[8:9]
	s_add_i32 s8, s46, -1
	s_mov_b32 s9, s19
	v_bfe_u32 v0, v158, 3, 3
	s_lshl_b64 s[16:17], s[8:9], 22
	s_ashr_i32 s9, s8, 31
	v_mul_u32_u24_e32 v1, 0x420, v1
	v_lshlrev_b32_e32 v4, 2, v0
	s_lshl_b64 s[20:21], s[18:19], 22
	s_lshl_b64 s[8:9], s[8:9], 22
	s_mul_i32 s25, s28, 0xb00000
	v_add_u32_e32 v60, s14, v2
	v_add3_u32 v65, s14, v1, v4
	s_mov_b64 s[14:15], 0x600000
	s_and_b64 s[6:7], s[6:7], exec
	s_mul_hi_u32 s24, s28, 0xb00000
	v_lshl_add_u64 v[42:43], v[36:37], 0, s[14:15]
	s_cselect_b32 s14, 0x800, 0
	s_add_u32 s6, s92, s25
	s_mul_i32 s36, s28, 0x1600000
	s_addc_u32 s7, s93, s24
	s_mul_hi_u32 s29, s28, 0x1600000
	v_lshl_add_u64 v[46:47], s[6:7], 0, v[2:3]
	s_add_u32 s6, s90, s36
	v_readlane_b32 s56, v250, 9
	s_addc_u32 s7, s91, s29
	v_readlane_b32 s57, v250, 10
	v_lshl_add_u64 v[48:49], s[6:7], 0, v[2:3]
	s_add_u32 s6, s56, s20
	s_addc_u32 s7, s57, s21
	s_add_u32 s16, s88, s16
	s_addc_u32 s17, s89, s17
	s_and_b64 s[4:5], s[4:5], exec
	v_readlane_b32 s62, v250, 15
	s_cselect_b32 s5, s7, s17
	s_cselect_b32 s4, s6, s16
	v_readlane_b32 s63, v250, 16
	v_lshl_add_u64 v[50:51], s[4:5], 0, v[2:3]
	s_add_u32 s4, s62, s8
	v_readlane_b32 s52, v250, 5
	s_mul_i32 s18, s28, 0xc00000
	s_addc_u32 s5, s63, s9
	v_readlane_b32 s53, v250, 6
	s_mul_hi_u32 s15, s28, 0xc00000
	v_lshl_add_u64 v[52:53], s[4:5], 0, v[2:3]
	s_add_u32 s4, s52, s18
	v_readlane_b32 s60, v250, 13
	v_readlane_b32 s61, v250, 14
	v_or_b32_e32 v66, 32, v0
	s_addc_u32 s5, s53, s15
	v_readlane_b32 s20, v249, 17
	v_readlane_b32 s24, v249, 19
	v_mul_u32_u24_e32 v61, 0x84, v0
	v_or_b32_e32 v62, 8, v0
	v_or_b32_e32 v63, 16, v0
	v_or_b32_e32 v64, 24, v0
	v_mul_u32_u24_e32 v67, 0x84, v66
	v_or_b32_e32 v68, 40, v0
	v_or_b32_e32 v69, 48, v0
	v_or_b32_e32 v70, 56, v0
	v_lshl_add_u64 v[44:45], s[60:61], 0, v[2:3]
	v_lshl_add_u64 v[54:55], s[4:5], 0, v[2:3]
	v_mov_b32_e32 v1, v3
	v_readlane_b32 s21, v249, 18
	v_readlane_b32 s25, v249, 20
	v_readlane_b32 s49, v250, 2
	v_readlane_b32 s54, v250, 7
	v_readlane_b32 s55, v250, 8
	v_readlane_b32 s58, v250, 11
	v_readlane_b32 s59, v250, 12
	s_branch .LBB0_217
